# same as previous best plus 64-byte alignment of the nine GEMM K-loop heads
# baseline (speedup 1.0000x reference)
; template <class Epi, class S_t>
; __device__ __forceinline__ void gemm_phase(LAS unsigned char* lds, int lda, int ldb, const S_t& S, const Epi& E) {
;     ...
; #pragma unroll
;         for (int a = 0; a < 2; ++a)
; #pragma unroll
;             for (int b = 0; b < 2; ++b)
; #pragma unroll
;                 for (int m = 0; m < 4; ++m)
; #pragma unroll
;                     for (int n = 0; n < 2; ++n) acc[a][b][m][n] = (f32x4){0.f, 0.f, 0.f, 0.f};
;         cur = nxt; cA = nA; cB = nB; ++ui;
.LBB0_132:
	s_add_u32 s16, s16, 0x80080
	s_addc_u32 s17, s17, 0
	s_add_u32 s0, s18, 0x100
	v_mov_b32_e32 v0, 0
	s_addc_u32 s1, s19, 0
	s_mov_b32 s9, -2
	v_mov_b32_e32 v1, v0
	v_mov_b32_e32 v2, v0
	v_mov_b32_e32 v3, v0
	v_mov_b32_e32 v32, v0
	v_mov_b32_e32 v33, v0
	v_mov_b32_e32 v34, v0
	v_mov_b32_e32 v35, v0
	v_mov_b32_e32 v4, v0
	v_mov_b32_e32 v5, v0
	v_mov_b32_e32 v6, v0
	v_mov_b32_e32 v7, v0
	v_mov_b32_e32 v36, v0
	v_mov_b32_e32 v37, v0
	v_mov_b32_e32 v38, v0
	v_mov_b32_e32 v39, v0
	v_mov_b32_e32 v8, v0
	v_mov_b32_e32 v9, v0
	v_mov_b32_e32 v10, v0
	v_mov_b32_e32 v11, v0
	v_mov_b32_e32 v40, v0
	v_mov_b32_e32 v41, v0
	v_mov_b32_e32 v42, v0
	v_mov_b32_e32 v43, v0
	v_mov_b32_e32 v12, v0
	v_mov_b32_e32 v13, v0
	v_mov_b32_e32 v14, v0
	v_mov_b32_e32 v15, v0
	v_mov_b32_e32 v44, v0
	v_mov_b32_e32 v45, v0
	v_mov_b32_e32 v46, v0
	v_mov_b32_e32 v47, v0
	v_mov_b32_e32 v64, v0
	v_mov_b32_e32 v65, v0
	v_mov_b32_e32 v66, v0
	v_mov_b32_e32 v67, v0
	v_mov_b32_e32 v96, v0
	v_mov_b32_e32 v97, v0
	v_mov_b32_e32 v98, v0
	v_mov_b32_e32 v99, v0
	v_mov_b32_e32 v68, v0
	v_mov_b32_e32 v69, v0
	v_mov_b32_e32 v70, v0
	v_mov_b32_e32 v71, v0
	v_mov_b32_e32 v100, v0
	v_mov_b32_e32 v101, v0
	v_mov_b32_e32 v102, v0
	v_mov_b32_e32 v103, v0
	v_mov_b32_e32 v72, v0
	v_mov_b32_e32 v73, v0
	v_mov_b32_e32 v74, v0
	v_mov_b32_e32 v75, v0
	v_mov_b32_e32 v104, v0
	v_mov_b32_e32 v105, v0
	v_mov_b32_e32 v106, v0
	v_mov_b32_e32 v107, v0
	v_mov_b32_e32 v76, v0
	v_mov_b32_e32 v77, v0
	v_mov_b32_e32 v78, v0
	v_mov_b32_e32 v79, v0
	v_mov_b32_e32 v108, v0
	v_mov_b32_e32 v109, v0
	v_mov_b32_e32 v110, v0
	v_mov_b32_e32 v111, v0
	v_mov_b32_e32 v16, v0
	v_mov_b32_e32 v17, v0
	v_mov_b32_e32 v18, v0
	v_mov_b32_e32 v19, v0
	v_mov_b32_e32 v48, v0
	v_mov_b32_e32 v49, v0
	v_mov_b32_e32 v50, v0
	v_mov_b32_e32 v51, v0
	v_mov_b32_e32 v20, v0
	v_mov_b32_e32 v21, v0
	v_mov_b32_e32 v22, v0
	v_mov_b32_e32 v23, v0
	v_mov_b32_e32 v52, v0
	v_mov_b32_e32 v53, v0
	v_mov_b32_e32 v54, v0
	v_mov_b32_e32 v55, v0
	v_mov_b32_e32 v24, v0
	v_mov_b32_e32 v25, v0
	v_mov_b32_e32 v26, v0
	v_mov_b32_e32 v27, v0
	v_mov_b32_e32 v56, v0
	v_mov_b32_e32 v57, v0
	v_mov_b32_e32 v58, v0
	v_mov_b32_e32 v59, v0
	v_mov_b32_e32 v28, v0
	v_mov_b32_e32 v29, v0
	v_mov_b32_e32 v30, v0
	v_mov_b32_e32 v31, v0
	v_mov_b32_e32 v60, v0
	v_mov_b32_e32 v61, v0
	v_mov_b32_e32 v62, v0
	v_mov_b32_e32 v63, v0
	v_mov_b32_e32 v80, v0
	v_mov_b32_e32 v81, v0
	v_mov_b32_e32 v82, v0
	v_mov_b32_e32 v83, v0
	v_mov_b32_e32 v112, v0
	v_mov_b32_e32 v113, v0
	v_mov_b32_e32 v114, v0
	v_mov_b32_e32 v115, v0
	v_mov_b32_e32 v84, v0
	v_mov_b32_e32 v85, v0
	v_mov_b32_e32 v86, v0
	v_mov_b32_e32 v87, v0
	v_mov_b32_e32 v116, v0
	v_mov_b32_e32 v117, v0
	v_mov_b32_e32 v118, v0
	v_mov_b32_e32 v119, v0
	v_mov_b32_e32 v88, v0
	v_mov_b32_e32 v89, v0
	v_mov_b32_e32 v90, v0
	v_mov_b32_e32 v91, v0
	v_mov_b32_e32 v120, v0
	v_mov_b32_e32 v121, v0
	v_mov_b32_e32 v122, v0
	v_mov_b32_e32 v123, v0
	v_mov_b32_e32 v92, v0
	v_mov_b32_e32 v93, v0
	v_mov_b32_e32 v94, v0
	v_mov_b32_e32 v95, v0
	v_mov_b32_e32 v124, v0
	v_mov_b32_e32 v125, v0
	v_mov_b32_e32 v126, v0
	v_mov_b32_e32 v127, v0
	.p2align	6

; template <class Epi, class S_t>
; __device__ __forceinline__ void gemm_phase(LAS unsigned char* lds, int lda, int ldb, const S_t& S, const Epi& E) {
;     ...
;         for (int t = 0; t < nt; t += 2) {
;             const bool last = (t == nt - 2);
;             const char* a1 = cA + (size_t)(t + 1) * kstep;
;             const char* a2 = last ? nA : cA + (size_t)(t + 2) * kstep; const char* b2 = last ? nB : cB + (size_t)(t + 2) * kstep;
;             const char* a3 = a2 + kstep; const char* b3 = b2 + kstep;
;     ...
; #pragma unroll
;         for (int a = 0; a < 2; ++a)
; #pragma unroll
;             for (int b = 0; b < 2; ++b)
; #pragma unroll
;                 for (int m = 0; m < 4; ++m)
; #pragma unroll
;                     for (int n = 0; n < 2; ++n) acc[a][b][m][n] = (f32x4){0.f, 0.f, 0.f, 0.f};
;         cur = nxt; cA = nA; cB = nB; ++ui;
.LBB0_235:
	s_add_u32 s54, s54, 0x80080
	s_addc_u32 s55, s55, 0
	s_add_u32 s0, s56, 0x100
	v_mov_b32_e32 v0, 0
	s_addc_u32 s1, s57, 0
	s_mov_b32 s7, -2
	v_mov_b32_e32 v1, v0
	v_mov_b32_e32 v2, v0
	v_mov_b32_e32 v3, v0
	v_mov_b32_e32 v4, v0
	v_mov_b32_e32 v5, v0
	v_mov_b32_e32 v6, v0
	v_mov_b32_e32 v7, v0
	v_mov_b32_e32 v16, v0
	v_mov_b32_e32 v17, v0
	v_mov_b32_e32 v18, v0
	v_mov_b32_e32 v19, v0
	v_mov_b32_e32 v20, v0
	v_mov_b32_e32 v21, v0
	v_mov_b32_e32 v22, v0
	v_mov_b32_e32 v23, v0
	v_mov_b32_e32 v32, v0
	v_mov_b32_e32 v33, v0
	v_mov_b32_e32 v34, v0
	v_mov_b32_e32 v35, v0
	v_mov_b32_e32 v36, v0
	v_mov_b32_e32 v37, v0
	v_mov_b32_e32 v38, v0
	v_mov_b32_e32 v39, v0
	v_mov_b32_e32 v48, v0
	v_mov_b32_e32 v49, v0
	v_mov_b32_e32 v50, v0
	v_mov_b32_e32 v51, v0
	v_mov_b32_e32 v52, v0
	v_mov_b32_e32 v53, v0
	v_mov_b32_e32 v54, v0
	v_mov_b32_e32 v55, v0
	v_mov_b32_e32 v8, v0
	v_mov_b32_e32 v9, v0
	v_mov_b32_e32 v10, v0
	v_mov_b32_e32 v11, v0
	v_mov_b32_e32 v12, v0
	v_mov_b32_e32 v13, v0
	v_mov_b32_e32 v14, v0
	v_mov_b32_e32 v15, v0
	v_mov_b32_e32 v24, v0
	v_mov_b32_e32 v25, v0
	v_mov_b32_e32 v26, v0
	v_mov_b32_e32 v27, v0
	v_mov_b32_e32 v28, v0
	v_mov_b32_e32 v29, v0
	v_mov_b32_e32 v30, v0
	v_mov_b32_e32 v31, v0
	v_mov_b32_e32 v40, v0
	v_mov_b32_e32 v41, v0
	v_mov_b32_e32 v42, v0
	v_mov_b32_e32 v43, v0
	v_mov_b32_e32 v44, v0
	v_mov_b32_e32 v45, v0
	v_mov_b32_e32 v46, v0
	v_mov_b32_e32 v47, v0
	v_mov_b32_e32 v56, v0
	v_mov_b32_e32 v57, v0
	v_mov_b32_e32 v58, v0
	v_mov_b32_e32 v59, v0
	v_mov_b32_e32 v60, v0
	v_mov_b32_e32 v61, v0
	v_mov_b32_e32 v62, v0
	v_mov_b32_e32 v63, v0
	v_mov_b32_e32 v64, v0
	v_mov_b32_e32 v65, v0
	v_mov_b32_e32 v66, v0
	v_mov_b32_e32 v67, v0
	v_mov_b32_e32 v68, v0
	v_mov_b32_e32 v69, v0
	v_mov_b32_e32 v70, v0
	v_mov_b32_e32 v71, v0
	v_mov_b32_e32 v80, v0
	v_mov_b32_e32 v81, v0
	v_mov_b32_e32 v82, v0
	v_mov_b32_e32 v83, v0
	v_mov_b32_e32 v84, v0
	v_mov_b32_e32 v85, v0
	v_mov_b32_e32 v86, v0
	v_mov_b32_e32 v87, v0
	v_mov_b32_e32 v96, v0
	v_mov_b32_e32 v97, v0
	v_mov_b32_e32 v98, v0
	v_mov_b32_e32 v99, v0
	v_mov_b32_e32 v100, v0
	v_mov_b32_e32 v101, v0
	v_mov_b32_e32 v102, v0
	v_mov_b32_e32 v103, v0
	v_mov_b32_e32 v112, v0
	v_mov_b32_e32 v113, v0
	v_mov_b32_e32 v114, v0
	v_mov_b32_e32 v115, v0
	v_mov_b32_e32 v116, v0
	v_mov_b32_e32 v117, v0
	v_mov_b32_e32 v118, v0
	v_mov_b32_e32 v119, v0
	v_mov_b32_e32 v72, v0
	v_mov_b32_e32 v73, v0
	v_mov_b32_e32 v74, v0
	v_mov_b32_e32 v75, v0
	v_mov_b32_e32 v76, v0
	v_mov_b32_e32 v77, v0
	v_mov_b32_e32 v78, v0
	v_mov_b32_e32 v79, v0
	v_mov_b32_e32 v88, v0
	v_mov_b32_e32 v89, v0
	v_mov_b32_e32 v90, v0
	v_mov_b32_e32 v91, v0
	v_mov_b32_e32 v92, v0
	v_mov_b32_e32 v93, v0
	v_mov_b32_e32 v94, v0
	v_mov_b32_e32 v95, v0
	v_mov_b32_e32 v104, v0
	v_mov_b32_e32 v105, v0
	v_mov_b32_e32 v106, v0
	v_mov_b32_e32 v107, v0
	v_mov_b32_e32 v108, v0
	v_mov_b32_e32 v109, v0
	v_mov_b32_e32 v110, v0
	v_mov_b32_e32 v111, v0
	v_mov_b32_e32 v120, v0
	v_mov_b32_e32 v121, v0
	v_mov_b32_e32 v122, v0
	v_mov_b32_e32 v123, v0
	v_mov_b32_e32 v124, v0
	v_mov_b32_e32 v125, v0
	v_mov_b32_e32 v126, v0
	v_mov_b32_e32 v127, v0
	.p2align	6

; template <class Epi, class S_t>
; __device__ __forceinline__ void gemm_phase(LAS unsigned char* lds, int lda, int ldb, const S_t& S, const Epi& E) {
;     ...
; #pragma unroll
;         for (int a = 0; a < 2; ++a)
; #pragma unroll
;             for (int b = 0; b < 2; ++b)
; #pragma unroll
;                 for (int m = 0; m < 4; ++m)
; #pragma unroll
;                     for (int n = 0; n < 2; ++n) acc[a][b][m][n] = (f32x4){0.f, 0.f, 0.f, 0.f};
;         cur = nxt; cA = nA; cB = nB; ++ui;
.LBB0_534:
	v_mov_b32_e32 v0, 0
	s_mov_b32 s0, 0
	s_mov_b64 s[62:63], -1
	s_mov_b64 s[66:67], 0
	v_mov_b32_e32 v1, v0
	v_mov_b32_e32 v2, v0
	v_mov_b32_e32 v3, v0
	v_mov_b32_e32 v4, v0
	v_mov_b32_e32 v5, v0
	v_mov_b32_e32 v6, v0
	v_mov_b32_e32 v7, v0
	v_mov_b32_e32 v12, v0
	v_mov_b32_e32 v13, v0
	v_mov_b32_e32 v14, v0
	v_mov_b32_e32 v15, v0
	v_mov_b32_e32 v20, v0
	v_mov_b32_e32 v21, v0
	v_mov_b32_e32 v22, v0
	v_mov_b32_e32 v23, v0
	v_mov_b32_e32 v28, v0
	v_mov_b32_e32 v29, v0
	v_mov_b32_e32 v30, v0
	v_mov_b32_e32 v31, v0
	v_mov_b32_e32 v36, v0
	v_mov_b32_e32 v37, v0
	v_mov_b32_e32 v38, v0
	v_mov_b32_e32 v39, v0
	v_mov_b32_e32 v44, v0
	v_mov_b32_e32 v45, v0
	v_mov_b32_e32 v46, v0
	v_mov_b32_e32 v47, v0
	v_mov_b32_e32 v52, v0
	v_mov_b32_e32 v53, v0
	v_mov_b32_e32 v54, v0
	v_mov_b32_e32 v55, v0
	v_mov_b32_e32 v8, v0
	v_mov_b32_e32 v9, v0
	v_mov_b32_e32 v10, v0
	v_mov_b32_e32 v11, v0
	v_mov_b32_e32 v16, v0
	v_mov_b32_e32 v17, v0
	v_mov_b32_e32 v18, v0
	v_mov_b32_e32 v19, v0
	v_mov_b32_e32 v24, v0
	v_mov_b32_e32 v25, v0
	v_mov_b32_e32 v26, v0
	v_mov_b32_e32 v27, v0
	v_mov_b32_e32 v32, v0
	v_mov_b32_e32 v33, v0
	v_mov_b32_e32 v34, v0
	v_mov_b32_e32 v35, v0
	v_mov_b32_e32 v40, v0
	v_mov_b32_e32 v41, v0
	v_mov_b32_e32 v42, v0
	v_mov_b32_e32 v43, v0
	v_mov_b32_e32 v48, v0
	v_mov_b32_e32 v49, v0
	v_mov_b32_e32 v50, v0
	v_mov_b32_e32 v51, v0
	v_mov_b32_e32 v56, v0
	v_mov_b32_e32 v57, v0
	v_mov_b32_e32 v58, v0
	v_mov_b32_e32 v59, v0
	v_mov_b32_e32 v60, v0
	v_mov_b32_e32 v61, v0
	v_mov_b32_e32 v62, v0
	v_mov_b32_e32 v63, v0
	v_mov_b32_e32 v64, v0
	v_mov_b32_e32 v65, v0
	v_mov_b32_e32 v66, v0
	v_mov_b32_e32 v67, v0
	v_mov_b32_e32 v68, v0
	v_mov_b32_e32 v69, v0
	v_mov_b32_e32 v70, v0
	v_mov_b32_e32 v71, v0
	v_mov_b32_e32 v80, v0
	v_mov_b32_e32 v81, v0
	v_mov_b32_e32 v82, v0
	v_mov_b32_e32 v83, v0
	v_mov_b32_e32 v84, v0
	v_mov_b32_e32 v85, v0
	v_mov_b32_e32 v86, v0
	v_mov_b32_e32 v87, v0
	v_mov_b32_e32 v88, v0
	v_mov_b32_e32 v89, v0
	v_mov_b32_e32 v90, v0
	v_mov_b32_e32 v91, v0
	v_mov_b32_e32 v92, v0
	v_mov_b32_e32 v93, v0
	v_mov_b32_e32 v94, v0
	v_mov_b32_e32 v95, v0
	v_mov_b32_e32 v96, v0
	v_mov_b32_e32 v97, v0
	v_mov_b32_e32 v98, v0
	v_mov_b32_e32 v99, v0
	v_mov_b32_e32 v104, v0
	v_mov_b32_e32 v105, v0
	v_mov_b32_e32 v106, v0
	v_mov_b32_e32 v107, v0
	v_mov_b32_e32 v72, v0
	v_mov_b32_e32 v73, v0
	v_mov_b32_e32 v74, v0
	v_mov_b32_e32 v75, v0
	v_mov_b32_e32 v76, v0
	v_mov_b32_e32 v77, v0
	v_mov_b32_e32 v78, v0
	v_mov_b32_e32 v79, v0
	v_mov_b32_e32 v100, v0
	v_mov_b32_e32 v101, v0
	v_mov_b32_e32 v102, v0
	v_mov_b32_e32 v103, v0
	v_mov_b32_e32 v108, v0
	v_mov_b32_e32 v109, v0
	v_mov_b32_e32 v110, v0
	v_mov_b32_e32 v111, v0
	v_mov_b32_e32 v112, v0
	v_mov_b32_e32 v113, v0
	v_mov_b32_e32 v114, v0
	v_mov_b32_e32 v115, v0
	v_mov_b32_e32 v116, v0
	v_mov_b32_e32 v117, v0
	v_mov_b32_e32 v118, v0
	v_mov_b32_e32 v119, v0
	v_mov_b32_e32 v120, v0
	v_mov_b32_e32 v121, v0
	v_mov_b32_e32 v122, v0
	v_mov_b32_e32 v123, v0
	v_mov_b32_e32 v124, v0
	v_mov_b32_e32 v125, v0
	v_mov_b32_e32 v126, v0
	v_mov_b32_e32 v127, v0
	.p2align	6

; template <class Epi, class S_t>
; __device__ __forceinline__ void gemm_phase(LAS unsigned char* lds, int lda, int ldb, const S_t& S, const Epi& E) {
;     ...
; #pragma unroll
;         for (int a = 0; a < 2; ++a)
; #pragma unroll
;             for (int b = 0; b < 2; ++b)
; #pragma unroll
;                 for (int m = 0; m < 4; ++m)
; #pragma unroll
;                     for (int n = 0; n < 2; ++n) acc[a][b][m][n] = (f32x4){0.f, 0.f, 0.f, 0.f};
;         cur = nxt; cA = nA; cB = nB; ++ui;
.LBB0_546:
	v_mov_b32_e32 v4, 0
	s_mov_b32 s0, 0
	s_mov_b64 s[66:67], -1
	s_mov_b64 s[68:69], 0
	v_mov_b32_e32 v5, v4
	v_mov_b32_e32 v6, v4
	v_mov_b32_e32 v7, v4
	v_mov_b32_e32 v0, v4
	v_mov_b32_e32 v1, v4
	v_mov_b32_e32 v2, v4
	v_mov_b32_e32 v3, v4
	v_mov_b32_e32 v20, v4
	v_mov_b32_e32 v21, v4
	v_mov_b32_e32 v22, v4
	v_mov_b32_e32 v23, v4
	v_mov_b32_e32 v16, v4
	v_mov_b32_e32 v17, v4
	v_mov_b32_e32 v18, v4
	v_mov_b32_e32 v19, v4
	v_mov_b32_e32 v44, v4
	v_mov_b32_e32 v45, v4
	v_mov_b32_e32 v46, v4
	v_mov_b32_e32 v47, v4
	v_mov_b32_e32 v40, v4
	v_mov_b32_e32 v41, v4
	v_mov_b32_e32 v42, v4
	v_mov_b32_e32 v43, v4
	v_mov_b32_e32 v84, v4
	v_mov_b32_e32 v85, v4
	v_mov_b32_e32 v86, v4
	v_mov_b32_e32 v87, v4
	v_mov_b32_e32 v80, v4
	v_mov_b32_e32 v81, v4
	v_mov_b32_e32 v82, v4
	v_mov_b32_e32 v83, v4
	v_mov_b32_e32 v8, v4
	v_mov_b32_e32 v9, v4
	v_mov_b32_e32 v10, v4
	v_mov_b32_e32 v11, v4
	v_mov_b32_e32 v12, v4
	v_mov_b32_e32 v13, v4
	v_mov_b32_e32 v14, v4
	v_mov_b32_e32 v15, v4
	v_mov_b32_e32 v24, v4
	v_mov_b32_e32 v25, v4
	v_mov_b32_e32 v26, v4
	v_mov_b32_e32 v27, v4
	v_mov_b32_e32 v28, v4
	v_mov_b32_e32 v29, v4
	v_mov_b32_e32 v30, v4
	v_mov_b32_e32 v31, v4
	v_mov_b32_e32 v60, v4
	v_mov_b32_e32 v61, v4
	v_mov_b32_e32 v62, v4
	v_mov_b32_e32 v63, v4
	v_mov_b32_e32 v72, v4
	v_mov_b32_e32 v73, v4
	v_mov_b32_e32 v74, v4
	v_mov_b32_e32 v75, v4
	v_mov_b32_e32 v88, v4
	v_mov_b32_e32 v89, v4
	v_mov_b32_e32 v90, v4
	v_mov_b32_e32 v91, v4
	v_mov_b32_e32 v92, v4
	v_mov_b32_e32 v93, v4
	v_mov_b32_e32 v94, v4
	v_mov_b32_e32 v95, v4
	v_mov_b32_e32 v104, v4
	v_mov_b32_e32 v105, v4
	v_mov_b32_e32 v106, v4
	v_mov_b32_e32 v107, v4
	v_mov_b32_e32 v100, v4
	v_mov_b32_e32 v101, v4
	v_mov_b32_e32 v102, v4
	v_mov_b32_e32 v103, v4
	v_mov_b32_e32 v124, v4
	v_mov_b32_e32 v125, v4
	v_mov_b32_e32 v126, v4
	v_mov_b32_e32 v127, v4
	v_mov_b32_e32 v120, v4
	v_mov_b32_e32 v121, v4
	v_mov_b32_e32 v122, v4
	v_mov_b32_e32 v123, v4
	v_mov_b32_e32 v144, v4
	v_mov_b32_e32 v145, v4
	v_mov_b32_e32 v146, v4
	v_mov_b32_e32 v147, v4
	v_mov_b32_e32 v140, v4
	v_mov_b32_e32 v141, v4
	v_mov_b32_e32 v142, v4
	v_mov_b32_e32 v143, v4
	v_mov_b32_e32 v164, v4
	v_mov_b32_e32 v165, v4
	v_mov_b32_e32 v166, v4
	v_mov_b32_e32 v167, v4
	v_mov_b32_e32 v160, v4
	v_mov_b32_e32 v161, v4
	v_mov_b32_e32 v162, v4
	v_mov_b32_e32 v163, v4
	v_mov_b32_e32 v108, v4
	v_mov_b32_e32 v109, v4
	v_mov_b32_e32 v110, v4
	v_mov_b32_e32 v111, v4
	v_mov_b32_e32 v112, v4
	v_mov_b32_e32 v113, v4
	v_mov_b32_e32 v114, v4
	v_mov_b32_e32 v115, v4
	v_mov_b32_e32 v128, v4
	v_mov_b32_e32 v129, v4
	v_mov_b32_e32 v130, v4
	v_mov_b32_e32 v131, v4
	v_mov_b32_e32 v132, v4
	v_mov_b32_e32 v133, v4
	v_mov_b32_e32 v134, v4
	v_mov_b32_e32 v135, v4
	v_mov_b32_e32 v148, v4
	v_mov_b32_e32 v149, v4
	v_mov_b32_e32 v150, v4
	v_mov_b32_e32 v151, v4
	v_mov_b32_e32 v152, v4
	v_mov_b32_e32 v153, v4
	v_mov_b32_e32 v154, v4
	v_mov_b32_e32 v155, v4
	v_mov_b32_e32 v168, v4
	v_mov_b32_e32 v169, v4
	v_mov_b32_e32 v170, v4
	v_mov_b32_e32 v171, v4
	v_mov_b32_e32 v172, v4
	v_mov_b32_e32 v173, v4
	v_mov_b32_e32 v174, v4
	v_mov_b32_e32 v175, v4
	.p2align	6

; template <class Epi, class S_t>
; __device__ __forceinline__ void gemm_phase(LAS unsigned char* lds, int lda, int ldb, const S_t& S, const Epi& E) {
;     ...
;         for (int t = 0; t < nt; t += 2) {
;             const bool last = (t == nt - 2);
;             const char* a1 = cA + (size_t)(t + 1) * kstep;
;             const char* a2 = last ? nA : cA + (size_t)(t + 2) * kstep; const char* b2 = last ? nB : cB + (size_t)(t + 2) * kstep;
;             const char* a3 = a2 + kstep; const char* b3 = b2 + kstep;
;     ...
; #pragma unroll
;         for (int a = 0; a < 2; ++a)
; #pragma unroll
;             for (int b = 0; b < 2; ++b)
; #pragma unroll
;                 for (int m = 0; m < 4; ++m)
; #pragma unroll
;                     for (int n = 0; n < 2; ++n) acc[a][b][m][n] = (f32x4){0.f, 0.f, 0.f, 0.f};
;         cur = nxt; cA = nA; cB = nB; ++ui;
.LBB0_944:
	s_add_u32 s60, s60, 0x40080
	s_addc_u32 s61, s61, 0
	s_add_u32 s0, s62, 0x100
	v_mov_b32_e32 v0, 0
	s_addc_u32 s1, s63, 0
	s_mov_b32 s43, -2
	v_mov_b32_e32 v1, v0
	v_mov_b32_e32 v2, v0
	v_mov_b32_e32 v3, v0
	v_mov_b32_e32 v4, v0
	v_mov_b32_e32 v5, v0
	v_mov_b32_e32 v6, v0
	v_mov_b32_e32 v7, v0
	v_mov_b32_e32 v12, v0
	v_mov_b32_e32 v13, v0
	v_mov_b32_e32 v14, v0
	v_mov_b32_e32 v15, v0
	v_mov_b32_e32 v20, v0
	v_mov_b32_e32 v21, v0
	v_mov_b32_e32 v22, v0
	v_mov_b32_e32 v23, v0
	v_mov_b32_e32 v28, v0
	v_mov_b32_e32 v29, v0
	v_mov_b32_e32 v30, v0
	v_mov_b32_e32 v31, v0
	v_mov_b32_e32 v36, v0
	v_mov_b32_e32 v37, v0
	v_mov_b32_e32 v38, v0
	v_mov_b32_e32 v39, v0
	v_mov_b32_e32 v44, v0
	v_mov_b32_e32 v45, v0
	v_mov_b32_e32 v46, v0
	v_mov_b32_e32 v47, v0
	v_mov_b32_e32 v52, v0
	v_mov_b32_e32 v53, v0
	v_mov_b32_e32 v54, v0
	v_mov_b32_e32 v55, v0
	v_mov_b32_e32 v8, v0
	v_mov_b32_e32 v9, v0
	v_mov_b32_e32 v10, v0
	v_mov_b32_e32 v11, v0
	v_mov_b32_e32 v16, v0
	v_mov_b32_e32 v17, v0
	v_mov_b32_e32 v18, v0
	v_mov_b32_e32 v19, v0
	v_mov_b32_e32 v24, v0
	v_mov_b32_e32 v25, v0
	v_mov_b32_e32 v26, v0
	v_mov_b32_e32 v27, v0
	v_mov_b32_e32 v32, v0
	v_mov_b32_e32 v33, v0
	v_mov_b32_e32 v34, v0
	v_mov_b32_e32 v35, v0
	v_mov_b32_e32 v40, v0
	v_mov_b32_e32 v41, v0
	v_mov_b32_e32 v42, v0
	v_mov_b32_e32 v43, v0
	v_mov_b32_e32 v48, v0
	v_mov_b32_e32 v49, v0
	v_mov_b32_e32 v50, v0
	v_mov_b32_e32 v51, v0
	v_mov_b32_e32 v56, v0
	v_mov_b32_e32 v57, v0
	v_mov_b32_e32 v58, v0
	v_mov_b32_e32 v59, v0
	v_mov_b32_e32 v60, v0
	v_mov_b32_e32 v61, v0
	v_mov_b32_e32 v62, v0
	v_mov_b32_e32 v63, v0
	v_mov_b32_e32 v64, v0
	v_mov_b32_e32 v65, v0
	v_mov_b32_e32 v66, v0
	v_mov_b32_e32 v67, v0
	v_mov_b32_e32 v68, v0
	v_mov_b32_e32 v69, v0
	v_mov_b32_e32 v70, v0
	v_mov_b32_e32 v71, v0
	v_mov_b32_e32 v76, v0
	v_mov_b32_e32 v77, v0
	v_mov_b32_e32 v78, v0
	v_mov_b32_e32 v79, v0
	v_mov_b32_e32 v84, v0
	v_mov_b32_e32 v85, v0
	v_mov_b32_e32 v86, v0
	v_mov_b32_e32 v87, v0
	v_mov_b32_e32 v92, v0
	v_mov_b32_e32 v93, v0
	v_mov_b32_e32 v94, v0
	v_mov_b32_e32 v95, v0
	v_mov_b32_e32 v100, v0
	v_mov_b32_e32 v101, v0
	v_mov_b32_e32 v102, v0
	v_mov_b32_e32 v103, v0
	v_mov_b32_e32 v104, v0
	v_mov_b32_e32 v105, v0
	v_mov_b32_e32 v106, v0
	v_mov_b32_e32 v107, v0
	v_mov_b32_e32 v112, v0
	v_mov_b32_e32 v113, v0
	v_mov_b32_e32 v114, v0
	v_mov_b32_e32 v115, v0
	v_mov_b32_e32 v72, v0
	v_mov_b32_e32 v73, v0
	v_mov_b32_e32 v74, v0
	v_mov_b32_e32 v75, v0
	v_mov_b32_e32 v80, v0
	v_mov_b32_e32 v81, v0
	v_mov_b32_e32 v82, v0
	v_mov_b32_e32 v83, v0
	v_mov_b32_e32 v88, v0
	v_mov_b32_e32 v89, v0
	v_mov_b32_e32 v90, v0
	v_mov_b32_e32 v91, v0
	v_mov_b32_e32 v96, v0
	v_mov_b32_e32 v97, v0
	v_mov_b32_e32 v98, v0
	v_mov_b32_e32 v99, v0
	v_mov_b32_e32 v108, v0
	v_mov_b32_e32 v109, v0
	v_mov_b32_e32 v110, v0
	v_mov_b32_e32 v111, v0
	v_mov_b32_e32 v116, v0
	v_mov_b32_e32 v117, v0
	v_mov_b32_e32 v118, v0
	v_mov_b32_e32 v119, v0
	v_mov_b32_e32 v120, v0
	v_mov_b32_e32 v121, v0
	v_mov_b32_e32 v122, v0
	v_mov_b32_e32 v123, v0
	v_mov_b32_e32 v124, v0
	v_mov_b32_e32 v125, v0
	v_mov_b32_e32 v126, v0
	v_mov_b32_e32 v127, v0
	.p2align	6

; template <class Epi, class S_t>
; __device__ __forceinline__ void gemm_phase(LAS unsigned char* lds, int lda, int ldb, const S_t& S, const Epi& E) {
;     ...
;         for (int t = 0; t < nt; t += 2) {
;             const bool last = (t == nt - 2);
;             const char* a1 = cA + (size_t)(t + 1) * kstep;
;             const char* a2 = last ? nA : cA + (size_t)(t + 2) * kstep; const char* b2 = last ? nB : cB + (size_t)(t + 2) * kstep;
;             const char* a3 = a2 + kstep; const char* b3 = b2 + kstep;
;     ...
; #pragma unroll
;         for (int a = 0; a < 2; ++a)
; #pragma unroll
;             for (int b = 0; b < 2; ++b)
; #pragma unroll
;                 for (int m = 0; m < 4; ++m)
; #pragma unroll
;                     for (int n = 0; n < 2; ++n) acc[a][b][m][n] = (f32x4){0.f, 0.f, 0.f, 0.f};
;         cur = nxt; cA = nA; cB = nB; ++ui;
.LBB0_965:
	s_add_u32 s56, s56, 0x80080
	s_addc_u32 s57, s57, 0
	s_add_u32 s0, s58, 0x100
	v_mov_b32_e32 v0, 0
	s_addc_u32 s1, s59, 0
	s_mov_b32 s43, -2
	v_mov_b32_e32 v1, v0
	v_mov_b32_e32 v2, v0
	v_mov_b32_e32 v3, v0
	v_mov_b32_e32 v4, v0
	v_mov_b32_e32 v5, v0
	v_mov_b32_e32 v6, v0
	v_mov_b32_e32 v7, v0
	v_mov_b32_e32 v16, v0
	v_mov_b32_e32 v17, v0
	v_mov_b32_e32 v18, v0
	v_mov_b32_e32 v19, v0
	v_mov_b32_e32 v20, v0
	v_mov_b32_e32 v21, v0
	v_mov_b32_e32 v22, v0
	v_mov_b32_e32 v23, v0
	v_mov_b32_e32 v32, v0
	v_mov_b32_e32 v33, v0
	v_mov_b32_e32 v34, v0
	v_mov_b32_e32 v35, v0
	v_mov_b32_e32 v36, v0
	v_mov_b32_e32 v37, v0
	v_mov_b32_e32 v38, v0
	v_mov_b32_e32 v39, v0
	v_mov_b32_e32 v48, v0
	v_mov_b32_e32 v49, v0
	v_mov_b32_e32 v50, v0
	v_mov_b32_e32 v51, v0
	v_mov_b32_e32 v52, v0
	v_mov_b32_e32 v53, v0
	v_mov_b32_e32 v54, v0
	v_mov_b32_e32 v55, v0
	v_mov_b32_e32 v8, v0
	v_mov_b32_e32 v9, v0
	v_mov_b32_e32 v10, v0
	v_mov_b32_e32 v11, v0
	v_mov_b32_e32 v12, v0
	v_mov_b32_e32 v13, v0
	v_mov_b32_e32 v14, v0
	v_mov_b32_e32 v15, v0
	v_mov_b32_e32 v24, v0
	v_mov_b32_e32 v25, v0
	v_mov_b32_e32 v26, v0
	v_mov_b32_e32 v27, v0
	v_mov_b32_e32 v28, v0
	v_mov_b32_e32 v29, v0
	v_mov_b32_e32 v30, v0
	v_mov_b32_e32 v31, v0
	v_mov_b32_e32 v40, v0
	v_mov_b32_e32 v41, v0
	v_mov_b32_e32 v42, v0
	v_mov_b32_e32 v43, v0
	v_mov_b32_e32 v44, v0
	v_mov_b32_e32 v45, v0
	v_mov_b32_e32 v46, v0
	v_mov_b32_e32 v47, v0
	v_mov_b32_e32 v56, v0
	v_mov_b32_e32 v57, v0
	v_mov_b32_e32 v58, v0
	v_mov_b32_e32 v59, v0
	v_mov_b32_e32 v60, v0
	v_mov_b32_e32 v61, v0
	v_mov_b32_e32 v62, v0
	v_mov_b32_e32 v63, v0
	v_mov_b32_e32 v64, v0
	v_mov_b32_e32 v65, v0
	v_mov_b32_e32 v66, v0
	v_mov_b32_e32 v67, v0
	v_mov_b32_e32 v68, v0
	v_mov_b32_e32 v69, v0
	v_mov_b32_e32 v70, v0
	v_mov_b32_e32 v71, v0
	v_mov_b32_e32 v80, v0
	v_mov_b32_e32 v81, v0
	v_mov_b32_e32 v82, v0
	v_mov_b32_e32 v83, v0
	v_mov_b32_e32 v84, v0
	v_mov_b32_e32 v85, v0
	v_mov_b32_e32 v86, v0
	v_mov_b32_e32 v87, v0
	v_mov_b32_e32 v96, v0
	v_mov_b32_e32 v97, v0
	v_mov_b32_e32 v98, v0
	v_mov_b32_e32 v99, v0
	v_mov_b32_e32 v100, v0
	v_mov_b32_e32 v101, v0
	v_mov_b32_e32 v102, v0
	v_mov_b32_e32 v103, v0
	v_mov_b32_e32 v112, v0
	v_mov_b32_e32 v113, v0
	v_mov_b32_e32 v114, v0
	v_mov_b32_e32 v115, v0
	v_mov_b32_e32 v116, v0
	v_mov_b32_e32 v117, v0
	v_mov_b32_e32 v118, v0
	v_mov_b32_e32 v119, v0
	v_mov_b32_e32 v72, v0
	v_mov_b32_e32 v73, v0
	v_mov_b32_e32 v74, v0
	v_mov_b32_e32 v75, v0
	v_mov_b32_e32 v76, v0
	v_mov_b32_e32 v77, v0
	v_mov_b32_e32 v78, v0
	v_mov_b32_e32 v79, v0
	v_mov_b32_e32 v88, v0
	v_mov_b32_e32 v89, v0
	v_mov_b32_e32 v90, v0
	v_mov_b32_e32 v91, v0
	v_mov_b32_e32 v92, v0
	v_mov_b32_e32 v93, v0
	v_mov_b32_e32 v94, v0
	v_mov_b32_e32 v95, v0
	v_mov_b32_e32 v104, v0
	v_mov_b32_e32 v105, v0
	v_mov_b32_e32 v106, v0
	v_mov_b32_e32 v107, v0
	v_mov_b32_e32 v108, v0
	v_mov_b32_e32 v109, v0
	v_mov_b32_e32 v110, v0
	v_mov_b32_e32 v111, v0
	v_mov_b32_e32 v120, v0
	v_mov_b32_e32 v121, v0
	v_mov_b32_e32 v122, v0
	v_mov_b32_e32 v123, v0
	v_mov_b32_e32 v124, v0
	v_mov_b32_e32 v125, v0
	v_mov_b32_e32 v126, v0
	v_mov_b32_e32 v127, v0
	.p2align	6

; template <class Epi, class S_t>
; __device__ __forceinline__ void gemm_phase(LAS unsigned char* lds, int lda, int ldb, const S_t& S, const Epi& E) {
;     ...
;         for (int t = 0; t < nt; t += 2) {
;             const bool last = (t == nt - 2);
;             const char* a1 = cA + (size_t)(t + 1) * kstep;
;             const char* a2 = last ? nA : cA + (size_t)(t + 2) * kstep; const char* b2 = last ? nB : cB + (size_t)(t + 2) * kstep;
;             const char* a3 = a2 + kstep; const char* b3 = b2 + kstep;
;     ...
; #pragma unroll
;         for (int a = 0; a < 2; ++a)
; #pragma unroll
;             for (int b = 0; b < 2; ++b)
; #pragma unroll
;                 for (int m = 0; m < 4; ++m)
; #pragma unroll
;                     for (int n = 0; n < 2; ++n) acc[a][b][m][n] = (f32x4){0.f, 0.f, 0.f, 0.f};
;         cur = nxt; cA = nA; cB = nB; ++ui;
.LBB0_1050:
	s_add_i32 s0, s42, -2
	s_add_u32 s60, s60, 0x80080
	s_addc_u32 s61, s61, 0
	s_add_u32 s1, s62, 0x100
	v_mov_b32_e32 v0, 0
	s_addc_u32 s69, s63, 0
	s_mov_b32 s62, 0
	v_mov_b32_e32 v1, v0
	v_mov_b32_e32 v2, v0
	v_mov_b32_e32 v3, v0
	v_mov_b32_e32 v4, v0
	v_mov_b32_e32 v5, v0
	v_mov_b32_e32 v6, v0
	v_mov_b32_e32 v7, v0
	v_mov_b32_e32 v8, v0
	v_mov_b32_e32 v9, v0
	v_mov_b32_e32 v10, v0
	v_mov_b32_e32 v11, v0
	v_mov_b32_e32 v16, v0
	v_mov_b32_e32 v17, v0
	v_mov_b32_e32 v18, v0
	v_mov_b32_e32 v19, v0
	v_mov_b32_e32 v24, v0
	v_mov_b32_e32 v25, v0
	v_mov_b32_e32 v26, v0
	v_mov_b32_e32 v27, v0
	v_mov_b32_e32 v32, v0
	v_mov_b32_e32 v33, v0
	v_mov_b32_e32 v34, v0
	v_mov_b32_e32 v35, v0
	v_mov_b32_e32 v40, v0
	v_mov_b32_e32 v41, v0
	v_mov_b32_e32 v42, v0
	v_mov_b32_e32 v43, v0
	v_mov_b32_e32 v48, v0
	v_mov_b32_e32 v49, v0
	v_mov_b32_e32 v50, v0
	v_mov_b32_e32 v51, v0
	v_mov_b32_e32 v12, v0
	v_mov_b32_e32 v13, v0
	v_mov_b32_e32 v14, v0
	v_mov_b32_e32 v15, v0
	v_mov_b32_e32 v20, v0
	v_mov_b32_e32 v21, v0
	v_mov_b32_e32 v22, v0
	v_mov_b32_e32 v23, v0
	v_mov_b32_e32 v28, v0
	v_mov_b32_e32 v29, v0
	v_mov_b32_e32 v30, v0
	v_mov_b32_e32 v31, v0
	v_mov_b32_e32 v36, v0
	v_mov_b32_e32 v37, v0
	v_mov_b32_e32 v38, v0
	v_mov_b32_e32 v39, v0
	v_mov_b32_e32 v44, v0
	v_mov_b32_e32 v45, v0
	v_mov_b32_e32 v46, v0
	v_mov_b32_e32 v47, v0
	v_mov_b32_e32 v52, v0
	v_mov_b32_e32 v53, v0
	v_mov_b32_e32 v54, v0
	v_mov_b32_e32 v55, v0
	v_mov_b32_e32 v56, v0
	v_mov_b32_e32 v57, v0
	v_mov_b32_e32 v58, v0
	v_mov_b32_e32 v59, v0
	v_mov_b32_e32 v60, v0
	v_mov_b32_e32 v61, v0
	v_mov_b32_e32 v62, v0
	v_mov_b32_e32 v63, v0
	v_mov_b32_e32 v64, v0
	v_mov_b32_e32 v65, v0
	v_mov_b32_e32 v66, v0
	v_mov_b32_e32 v67, v0
	v_mov_b32_e32 v68, v0
	v_mov_b32_e32 v69, v0
	v_mov_b32_e32 v70, v0
	v_mov_b32_e32 v71, v0
	v_mov_b32_e32 v76, v0
	v_mov_b32_e32 v77, v0
	v_mov_b32_e32 v78, v0
	v_mov_b32_e32 v79, v0
	v_mov_b32_e32 v84, v0
	v_mov_b32_e32 v85, v0
	v_mov_b32_e32 v86, v0
	v_mov_b32_e32 v87, v0
	v_mov_b32_e32 v92, v0
	v_mov_b32_e32 v93, v0
	v_mov_b32_e32 v94, v0
	v_mov_b32_e32 v95, v0
	v_mov_b32_e32 v100, v0
	v_mov_b32_e32 v101, v0
	v_mov_b32_e32 v102, v0
	v_mov_b32_e32 v103, v0
	v_mov_b32_e32 v108, v0
	v_mov_b32_e32 v109, v0
	v_mov_b32_e32 v110, v0
	v_mov_b32_e32 v111, v0
	v_mov_b32_e32 v116, v0
	v_mov_b32_e32 v117, v0
	v_mov_b32_e32 v118, v0
	v_mov_b32_e32 v119, v0
	v_mov_b32_e32 v72, v0
	v_mov_b32_e32 v73, v0
	v_mov_b32_e32 v74, v0
	v_mov_b32_e32 v75, v0
	v_mov_b32_e32 v80, v0
	v_mov_b32_e32 v81, v0
	v_mov_b32_e32 v82, v0
	v_mov_b32_e32 v83, v0
	v_mov_b32_e32 v88, v0
	v_mov_b32_e32 v89, v0
	v_mov_b32_e32 v90, v0
	v_mov_b32_e32 v91, v0
	v_mov_b32_e32 v96, v0
	v_mov_b32_e32 v97, v0
	v_mov_b32_e32 v98, v0
	v_mov_b32_e32 v99, v0
	v_mov_b32_e32 v104, v0
	v_mov_b32_e32 v105, v0
	v_mov_b32_e32 v106, v0
	v_mov_b32_e32 v107, v0
	v_mov_b32_e32 v112, v0
	v_mov_b32_e32 v113, v0
	v_mov_b32_e32 v114, v0
	v_mov_b32_e32 v115, v0
	v_mov_b32_e32 v120, v0
	v_mov_b32_e32 v121, v0
	v_mov_b32_e32 v122, v0
	v_mov_b32_e32 v123, v0
	v_mov_b32_e32 v124, v0
	v_mov_b32_e32 v125, v0
	v_mov_b32_e32 v126, v0
	v_mov_b32_e32 v127, v0
	.p2align	6

; template <class Epi, class S_t>
; __device__ __forceinline__ void gemm_phase(LAS unsigned char* lds, int lda, int ldb, const S_t& S, const Epi& E) {
;     ...
;         for (int t = 0; t < nt; t += 2) {
;             const bool last = (t == nt - 2);
;             const char* a1 = cA + (size_t)(t + 1) * kstep;
;             const char* a2 = last ? nA : cA + (size_t)(t + 2) * kstep; const char* b2 = last ? nB : cB + (size_t)(t + 2) * kstep;
;             const char* a3 = a2 + kstep; const char* b3 = b2 + kstep;
;     ...
; #pragma unroll
;         for (int a = 0; a < 2; ++a)
; #pragma unroll
;             for (int b = 0; b < 2; ++b)
; #pragma unroll
;                 for (int m = 0; m < 4; ++m)
; #pragma unroll
;                     for (int n = 0; n < 2; ++n) acc[a][b][m][n] = (f32x4){0.f, 0.f, 0.f, 0.f};
;         cur = nxt; cA = nA; cB = nB; ++ui;
.LBB0_1199:
	s_add_u32 s74, s74, 0x80080
	s_addc_u32 s75, s75, 0
	s_add_u32 s0, s76, 0x100
	v_mov_b32_e32 v0, 0
	s_addc_u32 s1, s77, 0
	s_mov_b32 s5, -2
	v_mov_b32_e32 v1, v0
	v_mov_b32_e32 v2, v0
	v_mov_b32_e32 v3, v0
	v_mov_b32_e32 v4, v0
	v_mov_b32_e32 v5, v0
	v_mov_b32_e32 v6, v0
	v_mov_b32_e32 v7, v0
	v_mov_b32_e32 v8, v0
	v_mov_b32_e32 v9, v0
	v_mov_b32_e32 v10, v0
	v_mov_b32_e32 v11, v0
	v_mov_b32_e32 v16, v0
	v_mov_b32_e32 v17, v0
	v_mov_b32_e32 v18, v0
	v_mov_b32_e32 v19, v0
	v_mov_b32_e32 v24, v0
	v_mov_b32_e32 v25, v0
	v_mov_b32_e32 v26, v0
	v_mov_b32_e32 v27, v0
	v_mov_b32_e32 v32, v0
	v_mov_b32_e32 v33, v0
	v_mov_b32_e32 v34, v0
	v_mov_b32_e32 v35, v0
	v_mov_b32_e32 v40, v0
	v_mov_b32_e32 v41, v0
	v_mov_b32_e32 v42, v0
	v_mov_b32_e32 v43, v0
	v_mov_b32_e32 v48, v0
	v_mov_b32_e32 v49, v0
	v_mov_b32_e32 v50, v0
	v_mov_b32_e32 v51, v0
	v_mov_b32_e32 v12, v0
	v_mov_b32_e32 v13, v0
	v_mov_b32_e32 v14, v0
	v_mov_b32_e32 v15, v0
	v_mov_b32_e32 v20, v0
	v_mov_b32_e32 v21, v0
	v_mov_b32_e32 v22, v0
	v_mov_b32_e32 v23, v0
	v_mov_b32_e32 v28, v0
	v_mov_b32_e32 v29, v0
	v_mov_b32_e32 v30, v0
	v_mov_b32_e32 v31, v0
	v_mov_b32_e32 v36, v0
	v_mov_b32_e32 v37, v0
	v_mov_b32_e32 v38, v0
	v_mov_b32_e32 v39, v0
	v_mov_b32_e32 v44, v0
	v_mov_b32_e32 v45, v0
	v_mov_b32_e32 v46, v0
	v_mov_b32_e32 v47, v0
	v_mov_b32_e32 v52, v0
	v_mov_b32_e32 v53, v0
	v_mov_b32_e32 v54, v0
	v_mov_b32_e32 v55, v0
	v_mov_b32_e32 v56, v0
	v_mov_b32_e32 v57, v0
	v_mov_b32_e32 v58, v0
	v_mov_b32_e32 v59, v0
	v_mov_b32_e32 v60, v0
	v_mov_b32_e32 v61, v0
	v_mov_b32_e32 v62, v0
	v_mov_b32_e32 v63, v0
	v_mov_b32_e32 v64, v0
	v_mov_b32_e32 v65, v0
	v_mov_b32_e32 v66, v0
	v_mov_b32_e32 v67, v0
	v_mov_b32_e32 v68, v0
	v_mov_b32_e32 v69, v0
	v_mov_b32_e32 v70, v0
	v_mov_b32_e32 v71, v0
	v_mov_b32_e32 v72, v0
	v_mov_b32_e32 v73, v0
	v_mov_b32_e32 v74, v0
	v_mov_b32_e32 v75, v0
	v_mov_b32_e32 v80, v0
	v_mov_b32_e32 v81, v0
	v_mov_b32_e32 v82, v0
	v_mov_b32_e32 v83, v0
	v_mov_b32_e32 v88, v0
	v_mov_b32_e32 v89, v0
	v_mov_b32_e32 v90, v0
	v_mov_b32_e32 v91, v0
	v_mov_b32_e32 v96, v0
	v_mov_b32_e32 v97, v0
	v_mov_b32_e32 v98, v0
	v_mov_b32_e32 v99, v0
	v_mov_b32_e32 v104, v0
	v_mov_b32_e32 v105, v0
	v_mov_b32_e32 v106, v0
	v_mov_b32_e32 v107, v0
	v_mov_b32_e32 v112, v0
	v_mov_b32_e32 v113, v0
	v_mov_b32_e32 v114, v0
	v_mov_b32_e32 v115, v0
	v_mov_b32_e32 v76, v0
	v_mov_b32_e32 v77, v0
	v_mov_b32_e32 v78, v0
	v_mov_b32_e32 v79, v0
	v_mov_b32_e32 v84, v0
	v_mov_b32_e32 v85, v0
	v_mov_b32_e32 v86, v0
	v_mov_b32_e32 v87, v0
	v_mov_b32_e32 v92, v0
	v_mov_b32_e32 v93, v0
	v_mov_b32_e32 v94, v0
	v_mov_b32_e32 v95, v0
	v_mov_b32_e32 v100, v0
	v_mov_b32_e32 v101, v0
	v_mov_b32_e32 v102, v0
	v_mov_b32_e32 v103, v0
	v_mov_b32_e32 v108, v0
	v_mov_b32_e32 v109, v0
	v_mov_b32_e32 v110, v0
	v_mov_b32_e32 v111, v0
	v_mov_b32_e32 v116, v0
	v_mov_b32_e32 v117, v0
	v_mov_b32_e32 v118, v0
	v_mov_b32_e32 v119, v0
	v_mov_b32_e32 v120, v0
	v_mov_b32_e32 v121, v0
	v_mov_b32_e32 v122, v0
	v_mov_b32_e32 v123, v0
	v_mov_b32_e32 v124, v0
	v_mov_b32_e32 v125, v0
	v_mov_b32_e32 v126, v0
	v_mov_b32_e32 v127, v0
	.p2align	6

; template <class Epi, class S_t>
; __device__ __forceinline__ void gemm_phase(LAS unsigned char* lds, int lda, int ldb, const S_t& S, const Epi& E) {
;     ...
;         for (int t = 0; t < nt; t += 2) {
;             const bool last = (t == nt - 2);
;             const char* a1 = cA + (size_t)(t + 1) * kstep;
;             const char* a2 = last ? nA : cA + (size_t)(t + 2) * kstep; const char* b2 = last ? nB : cB + (size_t)(t + 2) * kstep;
;             const char* a3 = a2 + kstep; const char* b3 = b2 + kstep;
;     ...
; #pragma unroll
;         for (int a = 0; a < 2; ++a)
; #pragma unroll
;             for (int b = 0; b < 2; ++b)
; #pragma unroll
;                 for (int m = 0; m < 4; ++m)
; #pragma unroll
;                     for (int n = 0; n < 2; ++n) acc[a][b][m][n] = (f32x4){0.f, 0.f, 0.f, 0.f};
;         cur = nxt; cA = nA; cB = nB; ++ui;
.LBB0_1382:
	s_add_i32 s0, s69, -2
	s_add_u32 s1, s48, 0x100
	v_mov_b32_e32 v0, 0
	s_addc_u32 s70, s49, 0
	s_mov_b32 s50, 0
	v_mov_b32_e32 v1, v0
	v_mov_b32_e32 v2, v0
	v_mov_b32_e32 v3, v0
	v_mov_b32_e32 v4, v0
	v_mov_b32_e32 v5, v0
	v_mov_b32_e32 v6, v0
	v_mov_b32_e32 v7, v0
	v_mov_b32_e32 v8, v0
	v_mov_b32_e32 v9, v0
	v_mov_b32_e32 v10, v0
	v_mov_b32_e32 v11, v0
	v_mov_b32_e32 v16, v0
	v_mov_b32_e32 v17, v0
	v_mov_b32_e32 v18, v0
	v_mov_b32_e32 v19, v0
	v_mov_b32_e32 v24, v0
	v_mov_b32_e32 v25, v0
	v_mov_b32_e32 v26, v0
	v_mov_b32_e32 v27, v0
	v_mov_b32_e32 v32, v0
	v_mov_b32_e32 v33, v0
	v_mov_b32_e32 v34, v0
	v_mov_b32_e32 v35, v0
	v_mov_b32_e32 v40, v0
	v_mov_b32_e32 v41, v0
	v_mov_b32_e32 v42, v0
	v_mov_b32_e32 v43, v0
	v_mov_b32_e32 v48, v0
	v_mov_b32_e32 v49, v0
	v_mov_b32_e32 v50, v0
	v_mov_b32_e32 v51, v0
	v_mov_b32_e32 v12, v0
	v_mov_b32_e32 v13, v0
	v_mov_b32_e32 v14, v0
	v_mov_b32_e32 v15, v0
	v_mov_b32_e32 v20, v0
	v_mov_b32_e32 v21, v0
	v_mov_b32_e32 v22, v0
	v_mov_b32_e32 v23, v0
	v_mov_b32_e32 v28, v0
	v_mov_b32_e32 v29, v0
	v_mov_b32_e32 v30, v0
	v_mov_b32_e32 v31, v0
	v_mov_b32_e32 v36, v0
	v_mov_b32_e32 v37, v0
	v_mov_b32_e32 v38, v0
	v_mov_b32_e32 v39, v0
	v_mov_b32_e32 v44, v0
	v_mov_b32_e32 v45, v0
	v_mov_b32_e32 v46, v0
	v_mov_b32_e32 v47, v0
	v_mov_b32_e32 v52, v0
	v_mov_b32_e32 v53, v0
	v_mov_b32_e32 v54, v0
	v_mov_b32_e32 v55, v0
	v_mov_b32_e32 v56, v0
	v_mov_b32_e32 v57, v0
	v_mov_b32_e32 v58, v0
	v_mov_b32_e32 v59, v0
	v_mov_b32_e32 v60, v0
	v_mov_b32_e32 v61, v0
	v_mov_b32_e32 v62, v0
	v_mov_b32_e32 v63, v0
	v_mov_b32_e32 v64, v0
	v_mov_b32_e32 v65, v0
	v_mov_b32_e32 v66, v0
	v_mov_b32_e32 v67, v0
	v_mov_b32_e32 v68, v0
	v_mov_b32_e32 v69, v0
	v_mov_b32_e32 v70, v0
	v_mov_b32_e32 v71, v0
	v_mov_b32_e32 v76, v0
	v_mov_b32_e32 v77, v0
	v_mov_b32_e32 v78, v0
	v_mov_b32_e32 v79, v0
	v_mov_b32_e32 v84, v0
	v_mov_b32_e32 v85, v0
	v_mov_b32_e32 v86, v0
	v_mov_b32_e32 v87, v0
	v_mov_b32_e32 v92, v0
	v_mov_b32_e32 v93, v0
	v_mov_b32_e32 v94, v0
	v_mov_b32_e32 v95, v0
	v_mov_b32_e32 v100, v0
	v_mov_b32_e32 v101, v0
	v_mov_b32_e32 v102, v0
	v_mov_b32_e32 v103, v0
	v_mov_b32_e32 v108, v0
	v_mov_b32_e32 v109, v0
	v_mov_b32_e32 v110, v0
	v_mov_b32_e32 v111, v0
	v_mov_b32_e32 v116, v0
	v_mov_b32_e32 v117, v0
	v_mov_b32_e32 v118, v0
	v_mov_b32_e32 v119, v0
	v_mov_b32_e32 v72, v0
	v_mov_b32_e32 v73, v0
	v_mov_b32_e32 v74, v0
	v_mov_b32_e32 v75, v0
	v_mov_b32_e32 v80, v0
	v_mov_b32_e32 v81, v0
	v_mov_b32_e32 v82, v0
	v_mov_b32_e32 v83, v0
	v_mov_b32_e32 v88, v0
	v_mov_b32_e32 v89, v0
	v_mov_b32_e32 v90, v0
	v_mov_b32_e32 v91, v0
	v_mov_b32_e32 v96, v0
	v_mov_b32_e32 v97, v0
	v_mov_b32_e32 v98, v0
	v_mov_b32_e32 v99, v0
	v_mov_b32_e32 v104, v0
	v_mov_b32_e32 v105, v0
	v_mov_b32_e32 v106, v0
	v_mov_b32_e32 v107, v0
	v_mov_b32_e32 v112, v0
	v_mov_b32_e32 v113, v0
	v_mov_b32_e32 v114, v0
	v_mov_b32_e32 v115, v0
	v_mov_b32_e32 v120, v0
	v_mov_b32_e32 v121, v0
	v_mov_b32_e32 v122, v0
	v_mov_b32_e32 v123, v0
	v_mov_b32_e32 v124, v0
	v_mov_b32_e32 v125, v0
	v_mov_b32_e32 v126, v0
	v_mov_b32_e32 v127, v0
	.p2align	6
